# v34: v32 + P5 first output-gate load issued before the state update (was right before the barrier)
# baseline (speedup 1.0000x reference)
; #define LAS __attribute__((address_space(3)))
; DI unsigned pk2(float lo, float hi) { f32x2 v = {lo, hi}; bfv2 b = __builtin_convertvector(v, bfv2); return __builtin_bit_cast(unsigned, b); }
; DI bf16_t f2bf(float x) { return (bf16_t)(pk2(x, 0.f) & 0xffffu); }
; #define MFMA16(a, b, c) __builtin_amdgcn_mfma_f32_16x16x32_bf16((a), (b), (c), 0, 0, 0)
; template <bool OUT> DI void hgrn_item(LAS unsigned char* lds, bf16_t* proj, float* hst, float* hdv, const float* normw, int item, bool dry) {
;     ...
;                 for (int r = 0; r < 4; ++r) { const int tt = 16 * ti + 4 * rq + r, ss = 16 * sj + e16; Ab[tt * TP + ss] = (sj <= ti && ss <= tt) ? f2bf(a[r]) : (bf16_t)0; }
;             }
; #pragma unroll
;             for (int ti = 0; ti < 4; ++ti) { o[ti] = (f32x4){0.f, 0.f, 0.f, 0.f};
; #pragma unroll
;                 for (int ks = 0; ks < 4; ++ks) { const LAS bf16_t* qp = Qt + (16 * ti + e16) * QP + 32 * ks + 4 * rq; const u32x2 q0 = *(const LAS u32x2*)qp, q1 = *(const LAS u32x2*)(qp + 16);
;                     u32x4 qa = {q0.x, q0.y, q1.x, q1.y};
;                     u32x4 sb; sb.x = pk2(st[2 * ks][0], st[2 * ks][1]); sb.y = pk2(st[2 * ks][2], st[2 * ks][3]); sb.z = pk2(st[2 * ks + 1][0], st[2 * ks + 1][1]); sb.w = pk2(st[2 * ks + 1][2], st[2 * ks + 1][3]);
;                     o[ti] = MFMA16(__builtin_bit_cast(bf16x8, qa), __builtin_bit_cast(bf16x8, sb), o[ti]); } }
;     ...
;         u32x4 gate8[2];
;         if (OUT) {
; #pragma unroll
;             for (int j = 0; j < 2; ++j) { const int cch = tid + 512 * j; gate8[j] = *(const u32x4*)(proj + (row0 + (cch >> 4)) * NPJ + C_HG + h * 128 + 8 * (cch & 15)); }
;         }
.LBB0_1170:
	v_or_b32_e32 v56, s14, v104
	v_cmp_gt_u32_e32 vcc, v120, v56
	s_or_b64 s[36:37], s[20:21], vcc
	s_nop 3
	v_cvt_pk_bf16_f32 v50, v50, s0
	v_cndmask_b32_e64 v50, v50, 0, s[36:37]
	v_mad_u64_u32 v[54:55], s[36:37], v56, s39, v[92:93]
	ds_write_b16 v54, v50
	v_or_b32_e32 v50, 1, v56
	v_cmp_gt_u32_e32 vcc, v120, v50
	s_or_b64 s[36:37], s[20:21], vcc
	v_cvt_pk_bf16_f32 v50, v51, s0
	v_cndmask_b32_e64 v50, v50, 0, s[36:37]
	ds_write_b16 v54, v50 offset:144
	v_or_b32_e32 v50, 2, v56
	v_cmp_gt_u32_e32 vcc, v120, v50
	s_or_b64 s[36:37], s[20:21], vcc
	v_cvt_pk_bf16_f32 v50, v52, s0
	v_cndmask_b32_e64 v50, v50, 0, s[36:37]
	ds_write_b16 v54, v50 offset:288
	v_or_b32_e32 v50, 3, v56
	v_cmp_gt_u32_e32 vcc, v120, v50
	s_or_b64 s[36:37], s[20:21], vcc
	v_cvt_pk_bf16_f32 v50, v53, s0
	v_cndmask_b32_e64 v50, v50, 0, s[36:37]
	ds_write_b16 v54, v50 offset:432
	ds_read2_b64 v[50:53], v115 offset1:4
	ds_read2_b64 v[54:57], v115 offset0:8 offset1:12
	s_waitcnt vmcnt(7)
	v_cvt_pk_bf16_f32 v66, v6, v7
	v_cvt_pk_bf16_f32 v67, v8, v9
	s_waitcnt vmcnt(6)
	v_cvt_pk_bf16_f32 v68, v10, v11
	v_cvt_pk_bf16_f32 v69, v12, v13
	s_waitcnt vmcnt(5)
	v_cvt_pk_bf16_f32 v70, v2, v3
	v_cvt_pk_bf16_f32 v71, v4, v5
	s_waitcnt lgkmcnt(1)
	v_mfma_f32_16x16x32_bf16 v[50:53], v[50:53], v[66:69], 0
	s_waitcnt vmcnt(4)
	v_cvt_pk_bf16_f32 v72, v18, v19
	v_cvt_pk_bf16_f32 v73, v20, v21
	s_waitcnt vmcnt(3)
	v_cvt_pk_bf16_f32 v100, v14, v15
	v_cvt_pk_bf16_f32 v101, v16, v17
	s_waitcnt lgkmcnt(0)
	v_mfma_f32_16x16x32_bf16 v[50:53], v[54:57], v[70:73], v[50:53]
	ds_read2_b64 v[54:57], v115 offset0:16 offset1:20
	s_waitcnt vmcnt(2)
	v_cvt_pk_bf16_f32 v102, v26, v27
	v_cvt_pk_bf16_f32 v103, v28, v29
	s_waitcnt vmcnt(1)
	v_cvt_pk_bf16_f32 v144, v22, v23
	v_cvt_pk_bf16_f32 v145, v24, v25
	s_waitcnt lgkmcnt(0)
	v_mfma_f32_16x16x32_bf16 v[50:53], v[54:57], v[100:103], v[50:53]
	ds_read2_b64 v[54:57], v115 offset0:24 offset1:28
	s_waitcnt vmcnt(0)
	v_cvt_pk_bf16_f32 v146, v30, v31
	v_cvt_pk_bf16_f32 v147, v32, v33
	v_lshl_add_u64 v[240:241], v[98:99], 0, s[34:35]
	v_add_co_u32_e32 v240, vcc, s47, v240
	s_nop 0
	v_addc_co_u32_e32 v241, vcc, 0, v241, vcc
	global_load_dwordx4 v[244:247], v[240:241], off offset:512
	v_add_u32_e32 v62, 0x1000, v115
	ds_read2_b64 v[58:61], v62 offset0:40 offset1:44
	s_waitcnt lgkmcnt(1)
	v_mfma_f32_16x16x32_bf16 v[54:57], v[54:57], v[144:147], v[50:53]
	s_nop 2
	ds_read2_b64 v[50:53], v62 offset0:32 offset1:36
	v_add_u32_e32 v143, 0x2000, v115
	s_waitcnt lgkmcnt(0)
	v_mfma_f32_16x16x32_bf16 v[50:53], v[50:53], v[66:69], 0
	v_mfma_f32_16x16x32_bf16 v[50:53], v[58:61], v[70:73], v[50:53]
	ds_read2_b64 v[58:61], v62 offset0:48 offset1:52
	s_waitcnt lgkmcnt(0)
	v_mfma_f32_16x16x32_bf16 v[50:53], v[58:61], v[100:103], v[50:53]
	ds_read2_b64 v[58:61], v62 offset0:56 offset1:60
	ds_read2_b64 v[62:65], v143 offset0:72 offset1:76
	s_waitcnt lgkmcnt(1)
	v_mfma_f32_16x16x32_bf16 v[58:61], v[58:61], v[144:147], v[50:53]
	s_nop 3
	ds_read2_b64 v[50:53], v143 offset0:64 offset1:68
	s_waitcnt lgkmcnt(0)
	v_mfma_f32_16x16x32_bf16 v[50:53], v[50:53], v[66:69], 0
	v_mfma_f32_16x16x32_bf16 v[50:53], v[62:65], v[70:73], v[50:53]
	ds_read2_b64 v[62:65], v143 offset0:80 offset1:84
	s_waitcnt lgkmcnt(0)
	v_mfma_f32_16x16x32_bf16 v[50:53], v[62:65], v[100:103], v[50:53]
	ds_read2_b64 v[62:65], v143 offset0:88 offset1:92
	v_add_u32_e32 v143, 0x3000, v115
	s_waitcnt lgkmcnt(0)
	v_mfma_f32_16x16x32_bf16 v[62:65], v[62:65], v[144:147], v[50:53]
	s_nop 3
	ds_read2_b64 v[50:53], v143 offset0:96 offset1:100
	s_waitcnt lgkmcnt(0)
	v_mfma_f32_16x16x32_bf16 v[50:53], v[50:53], v[66:69], 0
	ds_read2_b64 v[66:69], v143 offset0:104 offset1:108
	s_waitcnt lgkmcnt(0)
	v_mfma_f32_16x16x32_bf16 v[50:53], v[66:69], v[70:73], v[50:53]
	ds_read2_b64 v[66:69], v143 offset0:112 offset1:116
	s_waitcnt lgkmcnt(0)
	v_mfma_f32_16x16x32_bf16 v[50:53], v[66:69], v[100:103], v[50:53]
	ds_read2_b64 v[66:69], v143 offset0:120 offset1:124
	v_lshl_add_u64 v[102:103], v[98:99], 0, s[34:35]
	v_lshl_add_u64 v[100:101], v[96:97], 0, s[34:35]
	s_waitcnt lgkmcnt(0)
	v_mfma_f32_16x16x32_bf16 v[70:73], v[66:69], v[144:147], v[50:53]
	v_add_u32_e32 v66, v93, v108
	s_nop 1
	v_add_u32_e32 v67, 0x13c00, v93
	ds_read_b128 v[50:53], v66 offset:34816
	ds_read_b128 v[162:165], v66 offset:34880
	ds_read_b128 v[166:169], v67
	s_add_u32 s34, s34, 0xc8000
	s_addc_u32 s35, s35, 0
	s_cmp_lg_u32 s34, 0x320000
	ds_read_b128 v[170:173], v66 offset:37120
	ds_read_b128 v[174:177], v66 offset:37184
	ds_read_b128 v[178:181], v67 offset:64
	s_waitcnt lgkmcnt(3)
	v_mfma_f32_16x16x32_bf16 v[6:9], v[50:53], v[46:49], v[6:9]
	v_mfma_f32_16x16x32_bf16 v[6:9], v[162:165], v[42:45], v[6:9]
	s_nop 7
	v_pk_mul_f32 v[8:9], v[8:9], v[168:169]
	v_pk_mul_f32 v[6:7], v[6:7], v[166:167]
	ds_read_b128 v[50:53], v66 offset:39424
	ds_read_b128 v[162:165], v66 offset:39488
	ds_read_b128 v[166:169], v67 offset:128
	s_waitcnt lgkmcnt(3)
	v_mfma_f32_16x16x32_bf16 v[10:13], v[170:173], v[46:49], v[10:13]
	v_mfma_f32_16x16x32_bf16 v[10:13], v[174:177], v[42:45], v[10:13]
	s_nop 7
	v_pk_mul_f32 v[12:13], v[12:13], v[180:181]
	v_pk_mul_f32 v[10:11], v[10:11], v[178:179]
	ds_read_b128 v[170:173], v66 offset:41728
	ds_read_b128 v[174:177], v66 offset:41792
	ds_read_b128 v[178:181], v67 offset:192
	s_waitcnt lgkmcnt(3)
	v_mfma_f32_16x16x32_bf16 v[2:5], v[50:53], v[46:49], v[2:5]
	v_mfma_f32_16x16x32_bf16 v[2:5], v[162:165], v[42:45], v[2:5]
	s_nop 7
	v_pk_mul_f32 v[4:5], v[4:5], v[168:169]
	v_pk_mul_f32 v[2:3], v[2:3], v[166:167]
	ds_read_b128 v[50:53], v66 offset:44032
	ds_read_b128 v[162:165], v66 offset:44096
	ds_read_b128 v[166:169], v67 offset:256
	s_waitcnt lgkmcnt(3)
; #define LAS __attribute__((address_space(3)))
; #define MFMA16(a, b, c) __builtin_amdgcn_mfma_f32_16x16x32_bf16((a), (b), (c), 0, 0, 0)
; template <bool OUT> DI void hgrn_item(LAS unsigned char* lds, bf16_t* proj, float* hst, float* hdv, const float* normw, int item, bool dry) {
;     ...
;         for (int dt = 0; dt < 8; ++dt) {
; #pragma unroll
;             for (int ks = 0; ks < 2; ++ks) { const bf16x8 ka = *(const LAS bf16x8*)(KtT + (16 * dt + e16) * TP + 32 * ks + 8 * rq); st[dt] = MFMA16(ka, vfr[ks], st[dt]); }
;             const f32x4 dv = *(const LAS f32x4*)(Dv + 16 * dt + 4 * rq);
;             st[dt] *= dv;
;         }
;         u32x4 gate8[2];
;         if (OUT) {
; #pragma unroll
;             for (int j = 0; j < 2; ++j) { const int cch = tid + 512 * j; gate8[j] = *(const u32x4*)(proj + (row0 + (cch >> 4)) * NPJ + C_HG + h * 128 + 8 * (cch & 15)); }
;         }
;         __syncthreads();
;         if (OUT) {
; #pragma unroll
;             for (int ti = 0; ti < 4; ++ti)
; #pragma unroll
;                 for (int ks = 0; ks < 2; ++ks) if (2 * ks <= ti) { const bf16x8 aa = *(const LAS bf16x8*)(Ab + (16 * ti + e16) * TP + 32 * ks + 8 * rq); o[ti] = MFMA16(aa, vfr[ks], o[ti]); }
;             LAS float* Ob = (LAS float*)(lds + HOB_OFF);
; #pragma unroll
;             for (int ti = 0; ti < 4; ++ti)
; #pragma unroll
;                 for (int r = 0; r < 4; ++r) Ob[(16 * ti + 4 * rq + r) * OBP + w * 16 + e16] = o[ti][r];
	v_mfma_f32_16x16x32_bf16 v[18:21], v[170:173], v[46:49], v[18:21]
	v_mfma_f32_16x16x32_bf16 v[18:21], v[174:177], v[42:45], v[18:21]
	s_nop 7
	v_pk_mul_f32 v[20:21], v[20:21], v[180:181]
	v_pk_mul_f32 v[18:19], v[18:19], v[178:179]
	ds_read_b128 v[170:173], v66 offset:46336
	ds_read_b128 v[174:177], v66 offset:46400
	ds_read_b128 v[178:181], v67 offset:320
	s_waitcnt lgkmcnt(3)
	v_mfma_f32_16x16x32_bf16 v[14:17], v[50:53], v[46:49], v[14:17]
	v_mfma_f32_16x16x32_bf16 v[14:17], v[162:165], v[42:45], v[14:17]
	s_nop 7
	v_pk_mul_f32 v[16:17], v[16:17], v[168:169]
	v_pk_mul_f32 v[14:15], v[14:15], v[166:167]
	ds_read_b128 v[50:53], v66 offset:48640
	ds_read_b128 v[162:165], v66 offset:48704
	ds_read_b128 v[166:169], v67 offset:384
	s_waitcnt lgkmcnt(3)
	v_mfma_f32_16x16x32_bf16 v[26:29], v[170:173], v[46:49], v[26:29]
	v_mfma_f32_16x16x32_bf16 v[26:29], v[174:177], v[42:45], v[26:29]
	s_nop 7
	v_pk_mul_f32 v[28:29], v[28:29], v[180:181]
	v_pk_mul_f32 v[26:27], v[26:27], v[178:179]
	ds_read_b128 v[170:173], v66 offset:50944
	ds_read_b128 v[174:177], v66 offset:51008
	ds_read_b128 v[178:181], v67 offset:448
	s_waitcnt lgkmcnt(3)
	v_mfma_f32_16x16x32_bf16 v[22:25], v[50:53], v[46:49], v[22:25]
	v_mfma_f32_16x16x32_bf16 v[22:25], v[162:165], v[42:45], v[22:25]
	s_nop 7
	v_pk_mul_f32 v[24:25], v[24:25], v[168:169]
	v_pk_mul_f32 v[22:23], v[22:23], v[166:167]
	s_waitcnt lgkmcnt(0)
	v_mfma_f32_16x16x32_bf16 v[30:33], v[170:173], v[46:49], v[30:33]
	v_mfma_f32_16x16x32_bf16 v[30:33], v[174:177], v[42:45], v[30:33]
	s_nop 7
	v_pk_mul_f32 v[32:33], v[32:33], v[180:181]
	v_pk_mul_f32 v[30:31], v[30:31], v[178:179]
	v_add_co_u32_e32 v50, vcc, s47, v100
	s_nop 1
	v_addc_co_u32_e32 v51, vcc, 0, v101, vcc
	global_load_dwordx4 v[50:53], v[50:51], off offset:512
	s_barrier
	ds_read_b128 v[144:147], v116
	ds_read_b128 v[162:165], v116 offset:2304
	ds_read_b128 v[166:169], v116 offset:4608
	ds_read_b128 v[170:173], v116 offset:4672
	ds_read_b128 v[174:177], v116 offset:6912
	ds_read_b128 v[178:181], v116 offset:6976
	s_waitcnt lgkmcnt(5)
	v_mfma_f32_16x16x32_bf16 v[54:57], v[144:147], v[46:49], v[54:57]
	s_waitcnt lgkmcnt(4)
	v_mfma_f32_16x16x32_bf16 v[58:61], v[162:165], v[46:49], v[58:61]
	s_waitcnt lgkmcnt(3)
	v_mfma_f32_16x16x32_bf16 v[62:65], v[166:169], v[46:49], v[62:65]
	s_waitcnt lgkmcnt(2)
	v_mfma_f32_16x16x32_bf16 v[62:65], v[170:173], v[42:45], v[62:65]
	s_waitcnt lgkmcnt(1)
	v_mfma_f32_16x16x32_bf16 v[46:49], v[174:177], v[46:49], v[70:73]
	s_nop 2
	ds_write2_b32 v125, v54, v55 offset1:132
	s_waitcnt lgkmcnt(1)
	v_mfma_f32_16x16x32_bf16 v[42:45], v[178:181], v[42:45], v[46:49]
	s_nop 2
	v_add_u32_e32 v46, 0x400, v125
	ds_write2_b32 v46, v56, v57 offset0:8 offset1:140
	v_add_u32_e32 v46, 0x2000, v125
	ds_write2_b32 v46, v58, v59 offset0:64 offset1:196
	v_add_u32_e32 v46, 0x2400, v125
	ds_write2_b32 v46, v60, v61 offset0:72 offset1:204
	v_add_u32_e32 v46, 0x4200, v125
	ds_write2_b32 v46, v62, v63 offset1:132
	v_add_u32_e32 v46, 0x4600, v125
	ds_write2_b32 v46, v64, v65 offset0:8 offset1:140
	v_add_u32_e32 v46, 0x6200, v125
	ds_write2_b32 v46, v42, v43 offset0:64 offset1:196
	v_add_u32_e32 v42, 0x6600, v125
	ds_write2_b32 v42, v44, v45 offset0:72 offset1:204
	s_waitcnt lgkmcnt(0)
	s_barrier
; #define LAS __attribute__((address_space(3)))
; DI float bflo(unsigned w) { return __uint_as_float(w << 16); }
; DI float bfhi(unsigned w) { return __uint_as_float(w & 0xffff0000u); }
; DI u32x4 pack8(f32x4 a, f32x4 b) { u32x4 w; w.x = pk2(a[0], a[1]); w.y = pk2(a[2], a[3]); w.z = pk2(b[0], b[1]); w.w = pk2(b[2], b[3]); return w; }
; template <bool OUT> DI void hgrn_item(LAS unsigned char* lds, bf16_t* proj, float* hst, float* hdv, const float* normw, int item, bool dry) {
;     ...
; #pragma unroll
;             for (int j = 0; j < 2; ++j) { const int cch = tid + 512 * j, tt = cch >> 4, e0 = 8 * (cch & 15);
;                 const f32x4 a0 = *(const LAS f32x4*)(Ob + tt * OBP + e0), a1 = *(const LAS f32x4*)(Ob + tt * OBP + e0 + 4);
;                 float q = (a0[0] * a0[0] + a0[1] * a0[1]) + (a0[2] * a0[2] + a0[3] * a0[3]) + (a1[0] * a1[0] + a1[1] * a1[1]) + (a1[2] * a1[2] + a1[3] * a1[3]);
;                 q += __shfl_xor(q, 1); q += __shfl_xor(q, 2); q += __shfl_xor(q, 4); q += __shfl_xor(q, 8);
;                 const float rs = __builtin_amdgcn_rsqf(q * (1.0f / 128.0f) + 1e-6f);
;                 const f32x4 n0 = *(const f32x4*)(normw + e0), n1 = *(const f32x4*)(normw + e0 + 4); const u32x4 g = gate8[j];
;                 f32x4 y0, y1;
;                 y0[0] = a0[0] * rs * n0[0] * bflo(g.x); y0[1] = a0[1] * rs * n0[1] * bfhi(g.x); y0[2] = a0[2] * rs * n0[2] * bflo(g.y); y0[3] = a0[3] * rs * n0[3] * bfhi(g.y);
;                 y1[0] = a1[0] * rs * n1[0] * bflo(g.z); y1[1] = a1[1] * rs * n1[1] * bfhi(g.z); y1[2] = a1[2] * rs * n1[2] * bflo(g.w); y1[3] = a1[3] * rs * n1[3] * bfhi(g.w);
;                 if (!dry) *(u32x4*)(proj + (row0 + tt) * NPJ + C_HQ + h * 128 + e0) = pack8(y0, y1); }
	ds_read_b128 v[42:45], v117
	ds_read_b128 v[46:49], v117 offset:16
	s_waitcnt vmcnt(1)
	v_lshlrev_b32_e32 v64, 16, v246
	v_and_b32_e32 v65, 0xffff0000, v246
	s_waitcnt lgkmcnt(1)
	v_pk_mul_f32 v[54:55], v[44:45], v[44:45]
	v_pk_mul_f32 v[56:57], v[42:43], v[42:43]
	s_nop 0
	v_pk_mov_b32 v[58:59], v[56:57], v[54:55] op_sel:[1,0]
	v_mov_b32_e32 v57, v55
	v_pk_add_f32 v[54:55], v[58:59], v[56:57]
	s_waitcnt lgkmcnt(0)
	v_pk_mul_f32 v[56:57], v[48:49], v[48:49]
	v_pk_mul_f32 v[58:59], v[46:47], v[46:47]
	v_mov_b32_e32 v60, v56
	v_mov_b32_e32 v61, v58
	v_mov_b32_e32 v58, v57
	v_pk_add_f32 v[56:57], v[60:61], v[58:59]
	v_add_f32_e32 v54, v54, v55
	v_add_f32_e32 v54, v54, v57
	v_add_f32_e32 v54, v56, v54
	s_nop 1
	v_add_f32_dpp v54, v54, v54 quad_perm:[1,0,3,2] row_mask:0xf bank_mask:0xf
	s_nop 1
	v_add_f32_dpp v54, v54, v54 quad_perm:[2,3,0,1] row_mask:0xf bank_mask:0xf
	s_nop 1
	v_add_f32_dpp v62, v54, v54 row_half_mirror row_mask:0xf bank_mask:0xf
	s_nop 1
	v_add_f32_dpp v62, v62, v62 row_mirror row_mask:0xf bank_mask:0xf
	v_fmamk_f32 v62, v62, 0x3c000000, v118
	v_rsq_f32_e32 v62, v62
	s_nop 0
	v_pk_mul_f32 v[46:47], v[46:47], v[62:63] op_sel_hi:[1,0]
	v_pk_mul_f32 v[48:49], v[48:49], v[62:63] op_sel_hi:[1,0]
	v_pk_mul_f32 v[42:43], v[42:43], v[62:63] op_sel_hi:[1,0]
	v_pk_mul_f32 v[44:45], v[44:45], v[62:63] op_sel_hi:[1,0]
	s_waitcnt vmcnt(0)
	v_pk_mul_f32 v[42:43], v[232:233], v[42:43]
	v_pk_mul_f32 v[46:47], v[236:237], v[46:47]
	v_lshlrev_b32_e32 v58, 16, v247
	v_and_b32_e32 v59, 0xffff0000, v247
	v_pk_mul_f32 v[48:49], v[238:239], v[48:49]
	v_lshlrev_b32_e32 v54, 16, v245
	v_pk_mul_f32 v[48:49], v[48:49], v[58:59]
	v_lshlrev_b32_e32 v58, 16, v244
	v_and_b32_e32 v59, 0xffff0000, v244
	v_and_b32_e32 v55, 0xffff0000, v245
	v_pk_mul_f32 v[44:45], v[234:235], v[44:45]
	v_pk_mul_f32 v[46:47], v[46:47], v[64:65]
	v_pk_mul_f32 v[42:43], v[42:43], v[58:59]
	v_pk_mul_f32 v[44:45], v[44:45], v[54:55]
	v_cvt_pk_bf16_f32 v42, v42, v43
	v_cvt_pk_bf16_f32 v43, v44, v45
	v_cvt_pk_bf16_f32 v44, v46, v47
	v_cvt_pk_bf16_f32 v45, v48, v49
	global_store_dwordx4 v[102:103], v[42:45], off offset:1536
	ds_read_b128 v[42:45], v119
	ds_read_b128 v[46:49], v119 offset:16
	v_lshlrev_b32_e32 v64, 16, v52
	v_and_b32_e32 v65, 0xffff0000, v52
	v_lshlrev_b32_e32 v52, 16, v53
	s_waitcnt lgkmcnt(1)
	v_pk_mul_f32 v[54:55], v[44:45], v[44:45]
	v_pk_mul_f32 v[56:57], v[42:43], v[42:43]
	v_and_b32_e32 v53, 0xffff0000, v53
	v_pk_mov_b32 v[58:59], v[56:57], v[54:55] op_sel:[1,0]
	v_mov_b32_e32 v57, v55
	v_pk_add_f32 v[54:55], v[58:59], v[56:57]
	s_waitcnt lgkmcnt(0)
	v_pk_mul_f32 v[56:57], v[48:49], v[48:49]
	v_pk_mul_f32 v[58:59], v[46:47], v[46:47]
	v_mov_b32_e32 v60, v56
	v_mov_b32_e32 v61, v58
	v_mov_b32_e32 v58, v57
	v_pk_add_f32 v[56:57], v[60:61], v[58:59]
	v_add_f32_e32 v54, v54, v55
	v_add_f32_e32 v54, v54, v57
	v_add_f32_e32 v54, v56, v54
	s_nop 1
	v_add_f32_dpp v54, v54, v54 quad_perm:[1,0,3,2] row_mask:0xf bank_mask:0xf
	s_nop 1
	v_add_f32_dpp v54, v54, v54 quad_perm:[2,3,0,1] row_mask:0xf bank_mask:0xf
	s_nop 1
	v_add_f32_dpp v62, v54, v54 row_half_mirror row_mask:0xf bank_mask:0xf
	s_nop 1
	v_add_f32_dpp v62, v62, v62 row_mirror row_mask:0xf bank_mask:0xf
	v_fmamk_f32 v62, v62, 0x3c000000, v118
	v_rsq_f32_e32 v62, v62
	s_nop 0
	v_pk_mul_f32 v[48:49], v[48:49], v[62:63] op_sel_hi:[1,0]
	v_pk_mul_f32 v[46:47], v[46:47], v[62:63] op_sel_hi:[1,0]
	v_pk_mul_f32 v[42:43], v[42:43], v[62:63] op_sel_hi:[1,0]
	v_pk_mul_f32 v[44:45], v[44:45], v[62:63] op_sel_hi:[1,0]
	v_pk_mul_f32 v[42:43], v[232:233], v[42:43]
	v_pk_mul_f32 v[48:49], v[238:239], v[48:49]
	v_pk_mul_f32 v[46:47], v[236:237], v[46:47]
	v_pk_mul_f32 v[48:49], v[48:49], v[52:53]
	v_lshlrev_b32_e32 v52, 16, v50
	v_and_b32_e32 v53, 0xffff0000, v50
	v_lshlrev_b32_e32 v50, 16, v51
	v_and_b32_e32 v51, 0xffff0000, v51
	v_pk_mul_f32 v[44:45], v[234:235], v[44:45]
	v_pk_mul_f32 v[46:47], v[46:47], v[64:65]
	v_pk_mul_f32 v[42:43], v[42:43], v[52:53]
	v_pk_mul_f32 v[44:45], v[44:45], v[50:51]
	v_cvt_pk_bf16_f32 v42, v42, v43
	v_cvt_pk_bf16_f32 v43, v44, v45
	v_cvt_pk_bf16_f32 v44, v46, v47
	v_cvt_pk_bf16_f32 v45, v48, v49
	global_store_dwordx4 v[100:101], v[42:45], off offset:1536
	s_waitcnt vmcnt(1)
	v_lshl_or_b32 v129, v185, 16, v184
	v_lshl_or_b32 v127, v190, 16, v191
	v_lshl_or_b32 v131, v192, 16, v188
	v_lshl_or_b32 v128, v194, 16, v189
	v_lshl_or_b32 v133, v196, 16, v195
	v_lshl_or_b32 v135, v203, 16, v202
	v_lshl_or_b32 v134, v214, 16, v215
	v_lshl_or_b32 v34, v187, 16, v186
	v_lshl_or_b32 v35, v199, 16, v193
	v_lshl_or_b32 v36, v200, 16, v197
	v_lshl_or_b32 v130, v198, 16, v201
	v_lshl_or_b32 v37, v205, 16, v204
	v_lshl_or_b32 v132, v206, 16, v207
	v_lshl_or_b32 v137, v209, 16, v208
	v_lshl_or_b32 v38, v211, 16, v210
	v_lshl_or_b32 v139, v216, 16, v212
	v_lshl_or_b32 v136, v218, 16, v213
	v_lshl_or_b32 v141, v220, 16, v219
	v_lshl_or_b32 v39, v223, 16, v217
	v_lshl_or_b32 v40, v224, 16, v221
	v_lshl_or_b32 v138, v222, 16, v225
	v_lshl_or_b32 v142, v227, 16, v226
	v_lshl_or_b32 v41, v229, 16, v228
	v_lshl_or_b32 v140, v230, 16, v231
	v_mov_b32_e32 v46, v127
	v_mov_b32_e32 v47, v128
	v_mov_b32_e32 v49, v130
	v_mov_b32_e32 v51, v132
	v_mov_b32_e32 v52, v134
	v_mov_b32_e32 v53, v136
	v_mov_b32_e32 v54, v138
	v_mov_b32_e32 v48, v140
	v_mov_b32_e32 v42, v129
	v_mov_b32_e32 v43, v131
	v_mov_b32_e32 v44, v133
	v_mov_b32_e32 v45, v135
	v_mov_b32_e32 v50, v137
	v_mov_b32_e32 v55, v139
	v_mov_b32_e32 v56, v141
	v_mov_b32_e32 v57, v142
	s_cbranch_scc0 .LBB0_1168
